# IN GEMM K-loop: per-segment priority flips inverted (priority 1 in the load segments, 0 in the MFMA segments) instead of a static raise
# speedup vs baseline: 1.0070x; 1.0008x over previous
.LBB0_920:
	s_add_u32 s2, s70, 0xfffc0080
	s_addc_u32 s3, s71, -1
	s_add_i32 s9, 0, 0x10000
	s_cmp_eq_u32 vcc_hi, 12
	s_cselect_b32 s75, s14, s3
	s_cselect_b32 s74, s24, s2
	s_cselect_b32 s73, s59, vcc_lo
	s_cselect_b32 s72, s61, s63
	s_add_i32 s0, 0, 0x14000
	s_add_i32 m0, s69, 0xc000
	s_nop 0
	global_load_lds_dwordx4 v172, s[70:71]
	s_add_i32 m0, s69, 0xe000
	s_nop 0
	global_load_lds_dwordx4 v174, s[70:71]
	v_add_u32_e32 v2, s9, v188
	ds_read_b128 v[132:135], v2
	ds_read_b128 v[136:139], v2 offset:1024
	ds_read_b128 v[140:143], v2 offset:2048
	ds_read_b128 v[144:147], v2 offset:3072
	v_add_u32_e32 v2, s0, v188
	ds_read_b128 v[148:151], v2
	ds_read_b128 v[152:155], v2 offset:1024
	ds_read_b128 v[156:159], v2 offset:2048
	ds_read_b128 v[160:163], v2 offset:3072
	v_lshl_add_u64 v[184:185], s[70:71], 0, v[172:173]
	ds_read_b128 v[176:179], v189
	ds_read_b128 v[180:183], v189 offset:1024
	ds_read_b128 v[198:201], v189 offset:2048
	ds_read_b128 v[202:205], v189 offset:3072
	ds_read_b128 v[206:209], v189 offset:4096
	ds_read_b128 v[210:213], v189 offset:5120
	ds_read_b128 v[214:217], v189 offset:6144
	ds_read_b128 v[218:221], v189 offset:7168
	v_lshl_add_u64 v[184:185], s[70:71], 0, v[174:175]
	s_waitcnt vmcnt(8)
	s_waitcnt lgkmcnt(0)
	s_barrier
	s_setprio 0
	s_waitcnt lgkmcnt(0)
	v_mfma_f32_16x16x32_bf16 v[128:131], v[132:135], v[176:179], v[128:131]
	v_mfma_f32_16x16x32_bf16 v[124:127], v[140:143], v[176:179], v[124:127]
	v_mfma_f32_16x16x32_bf16 v[112:115], v[132:135], v[198:201], v[112:115]
	v_mfma_f32_16x16x32_bf16 v[108:111], v[140:143], v[198:201], v[108:111]
	v_mfma_f32_16x16x32_bf16 v[96:99], v[132:135], v[206:209], v[96:99]
	v_mfma_f32_16x16x32_bf16 v[92:95], v[140:143], v[206:209], v[92:95]
	v_mfma_f32_16x16x32_bf16 v[80:83], v[132:135], v[214:217], v[80:83]
	v_mfma_f32_16x16x32_bf16 v[76:79], v[140:143], v[214:217], v[76:79]
	v_mfma_f32_16x16x32_bf16 v[128:131], v[136:139], v[180:183], v[128:131]
	v_mfma_f32_16x16x32_bf16 v[124:127], v[144:147], v[180:183], v[124:127]
	v_mfma_f32_16x16x32_bf16 v[112:115], v[136:139], v[202:205], v[112:115]
	v_mfma_f32_16x16x32_bf16 v[108:111], v[144:147], v[202:205], v[108:111]
	v_mfma_f32_16x16x32_bf16 v[96:99], v[136:139], v[210:213], v[96:99]
	v_mfma_f32_16x16x32_bf16 v[92:95], v[144:147], v[210:213], v[92:95]
	v_mfma_f32_16x16x32_bf16 v[80:83], v[136:139], v[218:221], v[80:83]
	v_mfma_f32_16x16x32_bf16 v[76:79], v[144:147], v[218:221], v[76:79]
	s_setprio 1
	s_setprio 0
	v_mfma_f32_16x16x32_bf16 v[120:123], v[148:151], v[176:179], v[120:123]
	v_mfma_f32_16x16x32_bf16 v[116:119], v[156:159], v[176:179], v[116:119]
	v_mfma_f32_16x16x32_bf16 v[104:107], v[148:151], v[198:201], v[104:107]
	v_mfma_f32_16x16x32_bf16 v[100:103], v[156:159], v[198:201], v[100:103]
	v_mfma_f32_16x16x32_bf16 v[88:91], v[148:151], v[206:209], v[88:91]
	v_mfma_f32_16x16x32_bf16 v[84:87], v[156:159], v[206:209], v[84:87]
	v_mfma_f32_16x16x32_bf16 v[72:75], v[148:151], v[214:217], v[72:75]
	v_mfma_f32_16x16x32_bf16 v[68:71], v[156:159], v[214:217], v[68:71]
	v_mfma_f32_16x16x32_bf16 v[120:123], v[152:155], v[180:183], v[120:123]
	v_mfma_f32_16x16x32_bf16 v[116:119], v[160:163], v[180:183], v[116:119]
	v_mfma_f32_16x16x32_bf16 v[104:107], v[152:155], v[202:205], v[104:107]
	v_mfma_f32_16x16x32_bf16 v[100:103], v[160:163], v[202:205], v[100:103]
	v_mfma_f32_16x16x32_bf16 v[88:91], v[152:155], v[210:213], v[88:91]
	v_mfma_f32_16x16x32_bf16 v[84:87], v[160:163], v[210:213], v[84:87]
	v_mfma_f32_16x16x32_bf16 v[72:75], v[152:155], v[218:221], v[72:75]
	v_mfma_f32_16x16x32_bf16 v[68:71], v[160:163], v[218:221], v[68:71]
	s_setprio 1
	s_barrier
	s_add_i32 s2, s9, s80
	s_mov_b32 m0, s2
	s_nop 0
	global_load_lds_dwordx4 v166, s[72:73]
	s_add_i32 m0, s2, 0x2000
	s_add_u32 s2, s72, 0x40000
	s_addc_u32 s3, s73, 0
	s_add_i32 s0, s0, s80
	global_load_lds_dwordx4 v170, s[72:73]
	s_mov_b32 m0, s0
	s_nop 0
	global_load_lds_dwordx4 v166, s[2:3]
	s_add_i32 m0, s0, 0x2000
	s_nop 0
	global_load_lds_dwordx4 v170, s[2:3]
	s_mov_b32 m0, s69
	s_nop 0
	global_load_lds_dwordx4 v164, s[74:75]
	s_mov_b32 m0, s81
	s_nop 0
	global_load_lds_dwordx4 v168, s[74:75]
	v_lshl_add_u64 v[184:185], s[72:73], 0, v[166:167]
	ds_read_b128 v[176:179], v189 offset:16384
	ds_read_b128 v[180:183], v189 offset:17408
	ds_read_b128 v[198:201], v189 offset:18432
	ds_read_b128 v[202:205], v189 offset:19456
	ds_read_b128 v[206:209], v189 offset:20480
	ds_read_b128 v[210:213], v189 offset:21504
	ds_read_b128 v[214:217], v189 offset:22528
	ds_read_b128 v[218:221], v189 offset:23552
	v_lshl_add_u64 v[190:191], s[72:73], 0, v[170:171]
	v_lshl_add_u64 v[222:223], s[2:3], 0, v[166:167]
	v_lshl_add_u64 v[224:225], s[74:75], 0, v[168:169]
	v_lshl_add_u64 v[222:223], s[2:3], 0, v[170:171]
	v_lshl_add_u64 v[222:223], s[74:75], 0, v[164:165]
	s_waitcnt vmcnt(8)
	s_waitcnt lgkmcnt(0)
	s_barrier
	s_setprio 0
	s_waitcnt lgkmcnt(0)
	v_mfma_f32_16x16x32_bf16 v[64:67], v[132:135], v[176:179], v[64:67]
	v_mfma_f32_16x16x32_bf16 v[60:63], v[140:143], v[176:179], v[60:63]
	v_mfma_f32_16x16x32_bf16 v[48:51], v[132:135], v[198:201], v[48:51]
	v_mfma_f32_16x16x32_bf16 v[44:47], v[140:143], v[198:201], v[44:47]
	v_mfma_f32_16x16x32_bf16 v[32:35], v[132:135], v[206:209], v[32:35]
	v_mfma_f32_16x16x32_bf16 v[28:31], v[140:143], v[206:209], v[28:31]
	v_mfma_f32_16x16x32_bf16 v[16:19], v[132:135], v[214:217], v[16:19]
	v_mfma_f32_16x16x32_bf16 v[12:15], v[140:143], v[214:217], v[12:15]
	v_mfma_f32_16x16x32_bf16 v[64:67], v[136:139], v[180:183], v[64:67]
	v_mfma_f32_16x16x32_bf16 v[60:63], v[144:147], v[180:183], v[60:63]
	v_mfma_f32_16x16x32_bf16 v[48:51], v[136:139], v[202:205], v[48:51]
	v_mfma_f32_16x16x32_bf16 v[44:47], v[144:147], v[202:205], v[44:47]
	v_mfma_f32_16x16x32_bf16 v[32:35], v[136:139], v[210:213], v[32:35]
	v_mfma_f32_16x16x32_bf16 v[28:31], v[144:147], v[210:213], v[28:31]
	v_mfma_f32_16x16x32_bf16 v[16:19], v[136:139], v[218:221], v[16:19]
	v_mfma_f32_16x16x32_bf16 v[12:15], v[144:147], v[218:221], v[12:15]
	s_setprio 1
	s_setprio 0
	v_mfma_f32_16x16x32_bf16 v[56:59], v[148:151], v[176:179], v[56:59]
	v_mfma_f32_16x16x32_bf16 v[52:55], v[156:159], v[176:179], v[52:55]
	v_mfma_f32_16x16x32_bf16 v[40:43], v[148:151], v[198:201], v[40:43]
	v_mfma_f32_16x16x32_bf16 v[36:39], v[156:159], v[198:201], v[36:39]
	v_mfma_f32_16x16x32_bf16 v[24:27], v[148:151], v[206:209], v[24:27]
	v_mfma_f32_16x16x32_bf16 v[20:23], v[156:159], v[206:209], v[20:23]
	v_mfma_f32_16x16x32_bf16 v[8:11], v[148:151], v[214:217], v[8:11]
	v_mfma_f32_16x16x32_bf16 v[4:7], v[156:159], v[214:217], v[4:7]
	v_mfma_f32_16x16x32_bf16 v[56:59], v[152:155], v[180:183], v[56:59]
	v_mfma_f32_16x16x32_bf16 v[52:55], v[160:163], v[180:183], v[52:55]
	v_mfma_f32_16x16x32_bf16 v[40:43], v[152:155], v[202:205], v[40:43]
	v_mfma_f32_16x16x32_bf16 v[36:39], v[160:163], v[202:205], v[36:39]
	v_mfma_f32_16x16x32_bf16 v[24:27], v[152:155], v[210:213], v[24:27]
	v_mfma_f32_16x16x32_bf16 v[20:23], v[160:163], v[210:213], v[20:23]
	v_mfma_f32_16x16x32_bf16 v[8:11], v[152:155], v[218:221], v[8:11]
	v_mfma_f32_16x16x32_bf16 v[4:7], v[160:163], v[218:221], v[4:7]
	s_setprio 1
	s_barrier
	s_add_i32 s0, 0, 0x18000
	s_add_i32 s9, 0, 0x1c000
	s_add_u32 s2, s74, 0x40000
	s_addc_u32 s3, s75, 0
	s_mov_b32 m0, s88
	s_nop 0
	global_load_lds_dwordx4 v164, s[2:3]
	s_mov_b32 m0, s89
	s_nop 0
	global_load_lds_dwordx4 v168, s[2:3]
	v_add_u32_e32 v2, s0, v188
	ds_read_b128 v[132:135], v2
	ds_read_b128 v[136:139], v2 offset:1024
	ds_read_b128 v[140:143], v2 offset:2048
	ds_read_b128 v[144:147], v2 offset:3072
	v_add_u32_e32 v2, s9, v188
	ds_read_b128 v[148:151], v2
	ds_read_b128 v[152:155], v2 offset:1024
	ds_read_b128 v[156:159], v2 offset:2048
	ds_read_b128 v[160:163], v2 offset:3072
	v_lshl_add_u64 v[226:227], s[2:3], 0, v[164:165]
	ds_read_b128 v[176:179], v189 offset:32768
	ds_read_b128 v[180:183], v189 offset:33792
	ds_read_b128 v[198:201], v189 offset:34816
	ds_read_b128 v[202:205], v189 offset:35840
	ds_read_b128 v[206:209], v189 offset:36864
	ds_read_b128 v[210:213], v189 offset:37888
	ds_read_b128 v[214:217], v189 offset:38912
	ds_read_b128 v[218:221], v189 offset:39936
	v_lshl_add_u64 v[226:227], s[2:3], 0, v[168:169]
	s_waitcnt vmcnt(8)
	s_waitcnt lgkmcnt(0)
	s_barrier
	s_setprio 0
	s_waitcnt lgkmcnt(0)
	v_mfma_f32_16x16x32_bf16 v[128:131], v[132:135], v[176:179], v[128:131]
	v_mfma_f32_16x16x32_bf16 v[124:127], v[140:143], v[176:179], v[124:127]
	v_mfma_f32_16x16x32_bf16 v[112:115], v[132:135], v[198:201], v[112:115]
	v_mfma_f32_16x16x32_bf16 v[108:111], v[140:143], v[198:201], v[108:111]
	v_mfma_f32_16x16x32_bf16 v[96:99], v[132:135], v[206:209], v[96:99]
	v_mfma_f32_16x16x32_bf16 v[92:95], v[140:143], v[206:209], v[92:95]
	v_mfma_f32_16x16x32_bf16 v[80:83], v[132:135], v[214:217], v[80:83]
	v_mfma_f32_16x16x32_bf16 v[76:79], v[140:143], v[214:217], v[76:79]
	v_mfma_f32_16x16x32_bf16 v[128:131], v[136:139], v[180:183], v[128:131]
	v_mfma_f32_16x16x32_bf16 v[124:127], v[144:147], v[180:183], v[124:127]
	v_mfma_f32_16x16x32_bf16 v[112:115], v[136:139], v[202:205], v[112:115]
	v_mfma_f32_16x16x32_bf16 v[108:111], v[144:147], v[202:205], v[108:111]
	v_mfma_f32_16x16x32_bf16 v[96:99], v[136:139], v[210:213], v[96:99]
	v_mfma_f32_16x16x32_bf16 v[92:95], v[144:147], v[210:213], v[92:95]
	v_mfma_f32_16x16x32_bf16 v[80:83], v[136:139], v[218:221], v[80:83]
	v_mfma_f32_16x16x32_bf16 v[76:79], v[144:147], v[218:221], v[76:79]
	s_setprio 1
	s_setprio 0
	v_mfma_f32_16x16x32_bf16 v[120:123], v[148:151], v[176:179], v[120:123]
	v_mfma_f32_16x16x32_bf16 v[116:119], v[156:159], v[176:179], v[116:119]
	v_mfma_f32_16x16x32_bf16 v[104:107], v[148:151], v[198:201], v[104:107]
	v_mfma_f32_16x16x32_bf16 v[100:103], v[156:159], v[198:201], v[100:103]
	v_mfma_f32_16x16x32_bf16 v[88:91], v[148:151], v[206:209], v[88:91]
	v_mfma_f32_16x16x32_bf16 v[84:87], v[156:159], v[206:209], v[84:87]
	v_mfma_f32_16x16x32_bf16 v[72:75], v[148:151], v[214:217], v[72:75]
	v_mfma_f32_16x16x32_bf16 v[68:71], v[156:159], v[214:217], v[68:71]
	v_mfma_f32_16x16x32_bf16 v[120:123], v[152:155], v[180:183], v[120:123]
	v_mfma_f32_16x16x32_bf16 v[116:119], v[160:163], v[180:183], v[116:119]
	v_mfma_f32_16x16x32_bf16 v[104:107], v[152:155], v[202:205], v[104:107]
	v_mfma_f32_16x16x32_bf16 v[100:103], v[160:163], v[202:205], v[100:103]
	v_mfma_f32_16x16x32_bf16 v[88:91], v[152:155], v[210:213], v[88:91]
	v_mfma_f32_16x16x32_bf16 v[84:87], v[160:163], v[210:213], v[84:87]
	v_mfma_f32_16x16x32_bf16 v[72:75], v[152:155], v[218:221], v[72:75]
	v_mfma_f32_16x16x32_bf16 v[68:71], v[160:163], v[218:221], v[68:71]
	s_setprio 1
	s_barrier
	s_add_u32 s98, s72, 0x80
	s_addc_u32 s99, s73, 0
	s_add_u32 s100, s74, 0x80
	s_addc_u32 s101, s75, 0
	s_add_i32 s0, s0, s80
	s_mov_b32 m0, s0
	s_nop 0
	global_load_lds_dwordx4 v166, s[98:99]
	s_add_i32 m0, s0, 0x2000
	s_add_u32 s2, s72, 0x40080
	s_addc_u32 s3, s73, 0
	s_add_i32 s0, s9, s80
	global_load_lds_dwordx4 v170, s[98:99]
	s_mov_b32 m0, s0
	s_nop 0
	global_load_lds_dwordx4 v166, s[2:3]
	s_add_i32 m0, s0, 0x2000
	s_nop 0
	global_load_lds_dwordx4 v170, s[2:3]
	s_mov_b32 m0, s92
	s_nop 0
	global_load_lds_dwordx4 v164, s[100:101]
	s_mov_b32 m0, s93
	s_nop 0
	global_load_lds_dwordx4 v168, s[100:101]
	v_lshl_add_u64 v[184:185], v[184:185], 0, s[26:27]
	ds_read_b128 v[176:179], v189 offset:49152
	ds_read_b128 v[180:183], v189 offset:50176
	ds_read_b128 v[198:201], v189 offset:51200
	ds_read_b128 v[202:205], v189 offset:52224
	ds_read_b128 v[206:209], v189 offset:53248
	ds_read_b128 v[210:213], v189 offset:54272
	ds_read_b128 v[214:217], v189 offset:55296
	ds_read_b128 v[218:221], v189 offset:56320
	v_lshl_add_u64 v[184:185], v[190:191], 0, s[26:27]
	v_lshl_add_u64 v[184:185], s[2:3], 0, v[166:167]
	v_lshl_add_u64 v[184:185], s[2:3], 0, v[170:171]
	v_lshl_add_u64 v[184:185], v[222:223], 0, s[26:27]
	v_lshl_add_u64 v[184:185], v[224:225], 0, s[26:27]
	s_waitcnt vmcnt(8)
	s_waitcnt lgkmcnt(0)
	s_barrier
	s_setprio 0
	s_waitcnt lgkmcnt(0)
	v_mfma_f32_16x16x32_bf16 v[64:67], v[132:135], v[176:179], v[64:67]
	v_mfma_f32_16x16x32_bf16 v[60:63], v[140:143], v[176:179], v[60:63]
	v_mfma_f32_16x16x32_bf16 v[48:51], v[132:135], v[198:201], v[48:51]
	v_mfma_f32_16x16x32_bf16 v[44:47], v[140:143], v[198:201], v[44:47]
	v_mfma_f32_16x16x32_bf16 v[32:35], v[132:135], v[206:209], v[32:35]
	v_mfma_f32_16x16x32_bf16 v[28:31], v[140:143], v[206:209], v[28:31]
	v_mfma_f32_16x16x32_bf16 v[16:19], v[132:135], v[214:217], v[16:19]
	v_mfma_f32_16x16x32_bf16 v[12:15], v[140:143], v[214:217], v[12:15]
	v_mfma_f32_16x16x32_bf16 v[64:67], v[136:139], v[180:183], v[64:67]
	v_mfma_f32_16x16x32_bf16 v[60:63], v[144:147], v[180:183], v[60:63]
	v_mfma_f32_16x16x32_bf16 v[48:51], v[136:139], v[202:205], v[48:51]
	v_mfma_f32_16x16x32_bf16 v[44:47], v[144:147], v[202:205], v[44:47]
	v_mfma_f32_16x16x32_bf16 v[32:35], v[136:139], v[210:213], v[32:35]
	v_mfma_f32_16x16x32_bf16 v[28:31], v[144:147], v[210:213], v[28:31]
	v_mfma_f32_16x16x32_bf16 v[16:19], v[136:139], v[218:221], v[16:19]
	v_mfma_f32_16x16x32_bf16 v[12:15], v[144:147], v[218:221], v[12:15]
	s_setprio 1
	s_setprio 0
	v_mfma_f32_16x16x32_bf16 v[56:59], v[148:151], v[176:179], v[56:59]
	v_mfma_f32_16x16x32_bf16 v[52:55], v[156:159], v[176:179], v[52:55]
	v_mfma_f32_16x16x32_bf16 v[40:43], v[148:151], v[198:201], v[40:43]
	v_mfma_f32_16x16x32_bf16 v[36:39], v[156:159], v[198:201], v[36:39]
	v_mfma_f32_16x16x32_bf16 v[24:27], v[148:151], v[206:209], v[24:27]
	v_mfma_f32_16x16x32_bf16 v[20:23], v[156:159], v[206:209], v[20:23]
	v_mfma_f32_16x16x32_bf16 v[8:11], v[148:151], v[214:217], v[8:11]
	v_mfma_f32_16x16x32_bf16 v[4:7], v[156:159], v[214:217], v[4:7]
	v_mfma_f32_16x16x32_bf16 v[56:59], v[152:155], v[180:183], v[56:59]
	v_mfma_f32_16x16x32_bf16 v[52:55], v[160:163], v[180:183], v[52:55]
	v_mfma_f32_16x16x32_bf16 v[40:43], v[152:155], v[202:205], v[40:43]
	v_mfma_f32_16x16x32_bf16 v[36:39], v[160:163], v[202:205], v[36:39]
	v_mfma_f32_16x16x32_bf16 v[24:27], v[152:155], v[210:213], v[24:27]
	v_mfma_f32_16x16x32_bf16 v[20:23], v[160:163], v[210:213], v[20:23]
	v_mfma_f32_16x16x32_bf16 v[8:11], v[152:155], v[218:221], v[8:11]
	v_mfma_f32_16x16x32_bf16 v[4:7], v[160:163], v[218:221], v[4:7]
	s_setprio 1
	s_barrier
	s_add_i32 vcc_hi, vcc_hi, 2
	s_add_u32 s70, s70, 0x100
	s_addc_u32 s71, s71, 0
	s_add_u32 s63, s63, 0x100
	s_addc_u32 vcc_lo, vcc_lo, 0
	s_cmp_gt_u32 vcc_hi, 13
	s_cbranch_scc0 .LBB0_920
	s_setprio 0
	s_and_b64 vcc, exec, s[52:53]
	s_cbranch_vccz .LBB0_923
	s_barrier
